# third norm_rows loop copy: shift/scale vectors loaded once per iteration at loop top, serialized waits removed
# speedup vs baseline: 1.0132x; 1.0046x over previous
; __device__ __forceinline__ unsigned pk2(float lo, float hi) { return pg8::pk_bf16_rne(lo, hi); }
; __device__ __forceinline__ float wave_sum(float v) { v = row16_allsum(v); v = rows_pair_sum(v); v = halves_pair_sum(v); return v; }
; __device__ __forceinline__ void norm_rows(const Params& P, const float* src, float* copy_dst, int l, int shi, int gw, int NGW, int lane) {
;     ...
;     for (int m0 = 2 * gw; m0 < T; m0 += 2 * NGW) {
;         f32x4 v[2][4]; float s[2] = {0.f, 0.f};
; #pragma unroll
;         for (int q = 0; q < 2; ++q) { const f32x4* xr = (const f32x4*)(src + (size_t)(m0 + q) * D) + lane;
; #pragma unroll
;             for (int j = 0; j < 4; ++j) v[q][j] = xr[64 * j]; }
; #pragma unroll
;         for (int q = 0; q < 2; ++q) {
; #pragma unroll
;             for (int j = 0; j < 4; ++j) s[q] += (v[q][j].x * v[q][j].x + v[q][j].y * v[q][j].y) + (v[q][j].z * v[q][j].z + v[q][j].w * v[q][j].w); }
; #pragma unroll
;         for (int q = 0; q < 2; ++q) {
;             const int m = m0 + q, b = m >> 12;
;             const float rstd = 1.0f / sqrtf(wave_sum(s[q]) * (1.0f / D) + 1e-6f);
;             const f32x4* sh = (const f32x4*)(modl + (size_t)b * 9216 + shi * 1024) + lane;
;             const f32x4* sc = (const f32x4*)(modl + (size_t)b * 9216 + (shi + 1) * 1024) + lane;
;             u32x2* o8 = (u32x2*)(H + (size_t)m * D) + lane;
; #pragma unroll
;             for (int j = 0; j < 4; ++j) { const f32x4 a = sh[64 * j], c = sc[64 * j]; const f32x4 o = v[q][j] * rstd * (c + 1.0f) + a;
;                 u32x2 w; w.x = pk2(o.x, o.y); w.y = pk2(o.z, o.w); o8[64 * j] = w; }
;             if (copy_dst) { f32x4* cd = (f32x4*)(copy_dst + (size_t)m * D) + lane;
; #pragma unroll
;                 for (int j = 0; j < 4; ++j) cd[64 * j] = v[q][j]; }
.LBB0_1048:
	v_ashrrev_i32_e32 v100, 12, v32
	v_mul_hi_i32_i24_e32 v101, 0x9000, v100
	v_mul_i32_i24_e32 v100, 0x9000, v100
	v_lshl_add_u64 v[100:101], s[12:13], 0, v[100:101]
	v_lshl_add_u64 v[102:103], v[100:101], 0, v[152:153]
	v_lshl_add_u64 v[104:105], v[102:103], 0, s[24:25]
	global_load_dwordx4 v[60:63], v[102:103], off
	global_load_dwordx4 v[64:67], v[102:103], off offset:1024
	global_load_dwordx4 v[68:71], v[102:103], off offset:2048
	global_load_dwordx4 v[72:75], v[102:103], off offset:3072
	global_load_dwordx4 v[76:79], v[104:105], off
	global_load_dwordx4 v[80:83], v[104:105], off offset:1024
	global_load_dwordx4 v[84:87], v[104:105], off offset:2048
	global_load_dwordx4 v[88:91], v[104:105], off offset:3072
	v_lshl_add_u64 v[0:1], v[40:41], 0, v[34:35]
	global_load_dwordx4 v[16:19], v[0:1], off
	global_load_dwordx4 v[20:23], v[0:1], off offset:1024
	global_load_dwordx4 v[24:27], v[0:1], off offset:2048
	global_load_dwordx4 v[28:31], v[0:1], off offset:3072
	v_ashrrev_i32_e32 v2, 12, v32
	v_mul_hi_i32_i24_e32 v3, 0x9000, v2
	v_mul_i32_i24_e32 v2, 0x9000, v2
	v_lshl_add_u64 v[2:3], s[12:13], 0, v[2:3]
	v_lshl_add_u64 v[42:43], v[2:3], 0, v[152:153]
	v_add_co_u32_e32 v2, vcc, s36, v42
	s_waitcnt vmcnt(3)
	v_mul_f32_e32 v8, v17, v17
	v_addc_co_u32_e32 v3, vcc, 0, v43, vcc
	global_load_dwordx4 v[46:49], v[2:3], off
	global_load_dwordx4 v[50:53], v[42:43], off
	v_mul_f32_e32 v9, v19, v19
	s_waitcnt vmcnt(4)
	v_mul_f32_e32 v10, v21, v21
	v_mul_f32_e32 v11, v23, v23
	s_waitcnt vmcnt(3)
	v_mul_f32_e32 v14, v25, v25
	v_mul_f32_e32 v15, v27, v27
	v_fmac_f32_e32 v8, v16, v16
	v_fmac_f32_e32 v9, v18, v18
	v_fmac_f32_e32 v10, v20, v20
	v_fmac_f32_e32 v11, v22, v22
	s_waitcnt vmcnt(2)
	v_mul_f32_e32 v33, v29, v29
	v_mul_f32_e32 v44, v31, v31
	v_fmac_f32_e32 v14, v24, v24
	v_fmac_f32_e32 v15, v26, v26
	v_add_f32_e32 v8, v8, v9
	v_add_f32_e32 v9, v10, v11
	v_fmac_f32_e32 v33, v28, v28
	v_fmac_f32_e32 v44, v30, v30
	v_add_f32_e32 v10, v14, v15
	v_add_f32_e32 v8, v8, v9
	v_add_f32_e32 v11, v33, v44
	v_add_f32_e32 v8, v8, v10
	v_add_f32_e32 v8, v8, v11
	v_add_co_u32_e32 v12, vcc, 0x1000, v0
	s_nop 0
	v_add_f32_dpp v8, v8, v8 row_ror:8 row_mask:0xf bank_mask:0xf bound_ctrl:1
	v_addc_co_u32_e32 v13, vcc, 0, v1, vcc
	s_nop 0
	v_add_f32_dpp v8, v8, v8 row_ror:4 row_mask:0xf bank_mask:0xf bound_ctrl:1
	global_load_dwordx4 v[0:3], v[12:13], off
	global_load_dwordx4 v[4:7], v[12:13], off offset:1024
	v_add_f32_dpp v8, v8, v8 row_ror:2 row_mask:0xf bank_mask:0xf bound_ctrl:1
	v_lshl_add_u64 v[44:45], v[42:43], 0, s[24:25]
	s_waitcnt vmcnt(3)
	v_pk_add_f32 v[48:49], v[48:49], 1.0 op_sel_hi:[1,0]
	v_add_f32_dpp v8, v8, v8 row_ror:1 row_mask:0xf bank_mask:0xf bound_ctrl:1
	v_mov_b32_e32 v9, v8
	s_nop 1
	v_permlane16_swap_b32_e32 v8, v9
	v_add_f32_e32 v8, v8, v9
	v_mov_b32_e32 v9, v8
	s_nop 1
	v_permlane32_swap_b32_e32 v8, v9
	v_add_f32_e32 v8, v8, v9
	v_fmamk_f32 v8, v8, 0x3a800000, v155
	v_mul_f32_e32 v9, 0x4f800000, v8
	v_cmp_gt_f32_e32 vcc, s43, v8
	v_pk_add_f32 v[46:47], v[46:47], 1.0 op_sel_hi:[1,0]
	s_nop 0
	v_cndmask_b32_e32 v33, v8, v9, vcc
	v_sqrt_f32_e32 v54, v33
	global_load_dwordx4 v[8:11], v[12:13], off offset:2048
	s_nop 0
	global_load_dwordx4 v[12:15], v[12:13], off offset:3072
	v_add_u32_e32 v55, -1, v54
	v_add_u32_e32 v56, 1, v54
	v_fma_f32 v57, -v55, v54, v33
	v_fma_f32 v58, -v56, v54, v33
	v_cmp_ge_f32_e64 s[4:5], 0, v57
	s_nop 1
	v_cndmask_b32_e64 v54, v54, v55, s[4:5]
	v_cmp_lt_f32_e64 s[4:5], 0, v58
	s_nop 1
	v_cndmask_b32_e64 v54, v54, v56, s[4:5]
	v_mul_f32_e32 v55, 0x37800000, v54
	v_cndmask_b32_e32 v54, v54, v55, vcc
	v_cmp_class_f32_e32 vcc, v33, v175
	s_nop 1
	v_cndmask_b32_e32 v33, v54, v33, vcc
	v_div_scale_f32 v54, s[4:5], v33, v33, 1.0
	v_rcp_f32_e32 v55, v54
	v_div_scale_f32 v56, vcc, 1.0, v33, 1.0
	v_fma_f32 v57, -v54, v55, 1.0
	v_fmac_f32_e32 v55, v57, v55
	v_mul_f32_e32 v57, v56, v55
	v_fma_f32 v58, -v54, v57, v56
	v_fmac_f32_e32 v57, v58, v55
	v_fma_f32 v54, -v54, v57, v56
	v_div_fmas_f32 v54, v54, v55, v57
	v_div_fixup_f32 v54, v54, v33, 1.0
	v_pk_mul_f32 v[56:57], v[16:17], v[54:55] op_sel_hi:[1,0]
	v_pk_mul_f32 v[58:59], v[18:19], v[54:55] op_sel_hi:[1,0]
	s_waitcnt vmcnt(4)
	v_pk_fma_f32 v[46:47], v[46:47], v[56:57], v[50:51]
	v_pk_fma_f32 v[48:49], v[48:49], v[58:59], v[52:53]
	v_cvt_pk_bf16_f32 v46, v46, v47
	v_cvt_pk_bf16_f32 v47, v48, v49
	global_store_dwordx2 v[38:39], v[46:47], off offset:-3584
	s_nop 1
	v_mov_b64_e32 v[46:47], v[80:81]
	v_mov_b64_e32 v[48:49], v[82:83]
	s_nop 0
	v_mov_b64_e32 v[50:51], v[64:65]
	v_mov_b64_e32 v[52:53], v[66:67]
	v_pk_mul_f32 v[56:57], v[20:21], v[54:55] op_sel_hi:[1,0]
	v_pk_mul_f32 v[58:59], v[22:23], v[54:55] op_sel_hi:[1,0]
	v_cndmask_b32_e64 v33, 0, 1, s[14:15]
	v_cmp_ne_u32_e64 s[4:5], 1, v33
	s_andn2_b64 vcc, exec, s[14:15]
	s_waitcnt vmcnt(1)
	v_pk_add_f32 v[48:49], v[48:49], 1.0 op_sel_hi:[1,0]
	v_pk_add_f32 v[46:47], v[46:47], 1.0 op_sel_hi:[1,0]
	s_waitcnt vmcnt(0)
	v_pk_fma_f32 v[48:49], v[48:49], v[58:59], v[52:53]
	v_pk_fma_f32 v[46:47], v[46:47], v[56:57], v[50:51]
	v_pk_mul_f32 v[56:57], v[24:25], v[54:55] op_sel_hi:[1,0]
	v_cvt_pk_bf16_f32 v46, v46, v47
	v_cvt_pk_bf16_f32 v47, v48, v49
	global_store_dwordx2 v[38:39], v[46:47], off offset:-3072
	s_nop 1
	v_mov_b64_e32 v[46:47], v[84:85]
	v_mov_b64_e32 v[48:49], v[86:87]
	s_nop 0
	v_mov_b64_e32 v[50:51], v[68:69]
	v_mov_b64_e32 v[52:53], v[70:71]
	v_pk_mul_f32 v[58:59], v[26:27], v[54:55] op_sel_hi:[1,0]
	v_pk_add_f32 v[48:49], v[48:49], 1.0 op_sel_hi:[1,0]
	v_pk_add_f32 v[46:47], v[46:47], 1.0 op_sel_hi:[1,0]
	v_pk_fma_f32 v[48:49], v[48:49], v[58:59], v[52:53]
	v_pk_fma_f32 v[46:47], v[46:47], v[56:57], v[50:51]
	v_pk_mul_f32 v[56:57], v[28:29], v[54:55] op_sel_hi:[1,0]
	v_cvt_pk_bf16_f32 v46, v46, v47
	v_cvt_pk_bf16_f32 v47, v48, v49
	global_store_dwordx2 v[38:39], v[46:47], off offset:-2560
	s_nop 1
	v_mov_b64_e32 v[46:47], v[88:89]
	v_mov_b64_e32 v[48:49], v[90:91]
	s_nop 0
	v_mov_b64_e32 v[50:51], v[72:73]
	v_mov_b64_e32 v[52:53], v[74:75]
	v_pk_mul_f32 v[54:55], v[30:31], v[54:55] op_sel_hi:[1,0]
	v_pk_add_f32 v[48:49], v[48:49], 1.0 op_sel_hi:[1,0]
	v_pk_add_f32 v[46:47], v[46:47], 1.0 op_sel_hi:[1,0]
	v_pk_fma_f32 v[48:49], v[54:55], v[48:49], v[52:53]
	v_pk_fma_f32 v[46:47], v[56:57], v[46:47], v[50:51]
	s_nop 0
	v_cvt_pk_bf16_f32 v46, v46, v47
	v_cvt_pk_bf16_f32 v47, v48, v49
	global_store_dwordx2 v[38:39], v[46:47], off offset:-2048
	v_lshl_add_u64 v[46:47], v[36:37], 0, v[34:35]
	s_cbranch_vccnz .LBB0_1050
	global_store_dwordx4 v[46:47], v[16:19], off
	global_store_dwordx4 v[46:47], v[20:23], off offset:1024
	global_store_dwordx4 v[46:47], v[24:27], off offset:2048
	global_store_dwordx4 v[46:47], v[28:31], off offset:3072
; __device__ __forceinline__ unsigned pk2(float lo, float hi) { return pg8::pk_bf16_rne(lo, hi); }
; __device__ __forceinline__ float wave_sum(float v) { v = row16_allsum(v); v = rows_pair_sum(v); v = halves_pair_sum(v); return v; }
; __device__ __forceinline__ void norm_rows(const Params& P, const float* src, float* copy_dst, int l, int shi, int gw, int NGW, int lane) {
;     ...
;         for (int q = 0; q < 2; ++q) {
;             const int m = m0 + q, b = m >> 12;
;             const float rstd = 1.0f / sqrtf(wave_sum(s[q]) * (1.0f / D) + 1e-6f);
;             const f32x4* sh = (const f32x4*)(modl + (size_t)b * 9216 + shi * 1024) + lane;
;             const f32x4* sc = (const f32x4*)(modl + (size_t)b * 9216 + (shi + 1) * 1024) + lane;
;             u32x2* o8 = (u32x2*)(H + (size_t)m * D) + lane;
; #pragma unroll
;             for (int j = 0; j < 4; ++j) { const f32x4 a = sh[64 * j], c = sc[64 * j]; const f32x4 o = v[q][j] * rstd * (c + 1.0f) + a;
;                 u32x2 w; w.x = pk2(o.x, o.y); w.y = pk2(o.z, o.w); o8[64 * j] = w; }
;             if (copy_dst) { f32x4* cd = (f32x4*)(copy_dst + (size_t)m * D) + lane;
; #pragma unroll
;                 for (int j = 0; j < 4; ++j) cd[64 * j] = v[q][j]; }
.LBB0_1050:
	s_nop 1
	v_mov_b64_e32 v[16:17], v[76:77]
	v_mov_b64_e32 v[18:19], v[78:79]
	s_nop 0
	v_mov_b64_e32 v[20:21], v[60:61]
	v_mov_b64_e32 v[22:23], v[62:63]
	v_mul_f32_e32 v24, v1, v1
	v_mul_f32_e32 v25, v3, v3
	v_mul_f32_e32 v26, v5, v5
	v_mul_f32_e32 v27, v7, v7
	v_mul_f32_e32 v28, v9, v9
	v_mul_f32_e32 v29, v11, v11
	v_fmac_f32_e32 v24, v0, v0
	v_fmac_f32_e32 v25, v2, v2
	v_fmac_f32_e32 v26, v4, v4
	v_fmac_f32_e32 v27, v6, v6
	v_mul_f32_e32 v30, v13, v13
	v_mul_f32_e32 v31, v15, v15
	v_fmac_f32_e32 v28, v8, v8
	v_fmac_f32_e32 v29, v10, v10
	v_add_f32_e32 v24, v24, v25
	v_add_f32_e32 v25, v26, v27
	v_fmac_f32_e32 v30, v12, v12
	v_fmac_f32_e32 v31, v14, v14
	v_add_f32_e32 v26, v28, v29
	v_add_f32_e32 v24, v24, v25
	v_add_f32_e32 v27, v30, v31
	v_add_f32_e32 v24, v24, v26
	v_add_f32_e32 v24, v24, v27
	v_pk_add_f32 v[18:19], v[18:19], 1.0 op_sel_hi:[1,0]
	v_add_f32_dpp v24, v24, v24 row_ror:8 row_mask:0xf bank_mask:0xf bound_ctrl:1
	v_pk_add_f32 v[16:17], v[16:17], 1.0 op_sel_hi:[1,0]
	s_nop 0
	v_add_f32_dpp v24, v24, v24 row_ror:4 row_mask:0xf bank_mask:0xf bound_ctrl:1
	s_nop 1
	v_add_f32_dpp v24, v24, v24 row_ror:2 row_mask:0xf bank_mask:0xf bound_ctrl:1
	s_nop 1
	v_add_f32_dpp v24, v24, v24 row_ror:1 row_mask:0xf bank_mask:0xf bound_ctrl:1
	v_mov_b32_e32 v25, v24
	s_nop 1
	v_permlane16_swap_b32_e32 v24, v25
	v_add_f32_e32 v24, v24, v25
	v_mov_b32_e32 v25, v24
	s_nop 1
	v_permlane32_swap_b32_e32 v24, v25
	v_add_f32_e32 v24, v24, v25
	v_fmamk_f32 v24, v24, 0x3a800000, v155
	v_mul_f32_e32 v25, 0x4f800000, v24
	v_cmp_gt_f32_e32 vcc, s43, v24
	s_nop 1
	v_cndmask_b32_e32 v24, v24, v25, vcc
	v_sqrt_f32_e32 v25, v24
	s_nop 0
	v_add_u32_e32 v26, -1, v25
	v_add_u32_e32 v27, 1, v25
	v_fma_f32 v28, -v26, v25, v24
	v_fma_f32 v29, -v27, v25, v24
	v_cmp_ge_f32_e64 s[6:7], 0, v28
	s_nop 1
	v_cndmask_b32_e64 v25, v25, v26, s[6:7]
	v_cmp_lt_f32_e64 s[6:7], 0, v29
	s_nop 1
	v_cndmask_b32_e64 v25, v25, v27, s[6:7]
	v_mul_f32_e32 v26, 0x37800000, v25
	v_cndmask_b32_e32 v25, v25, v26, vcc
	v_cmp_class_f32_e32 vcc, v24, v175
	s_nop 1
	v_cndmask_b32_e32 v24, v25, v24, vcc
	v_div_scale_f32 v25, s[6:7], v24, v24, 1.0
	v_rcp_f32_e32 v26, v25
	v_div_scale_f32 v27, vcc, 1.0, v24, 1.0
	v_fma_f32 v28, -v25, v26, 1.0
	v_fmac_f32_e32 v26, v28, v26
	v_mul_f32_e32 v28, v27, v26
	v_fma_f32 v29, -v25, v28, v27
	v_fmac_f32_e32 v28, v29, v26
	v_fma_f32 v25, -v25, v28, v27
	v_div_fmas_f32 v25, v25, v26, v28
	v_div_fixup_f32 v24, v25, v24, 1.0
	v_pk_mul_f32 v[26:27], v[0:1], v[24:25] op_sel_hi:[1,0]
	v_pk_mul_f32 v[28:29], v[2:3], v[24:25] op_sel_hi:[1,0]
	v_pk_fma_f32 v[16:17], v[16:17], v[26:27], v[20:21]
	v_pk_fma_f32 v[18:19], v[18:19], v[28:29], v[22:23]
	v_cvt_pk_bf16_f32 v16, v16, v17
	v_cvt_pk_bf16_f32 v17, v18, v19
	global_store_dwordx2 v[38:39], v[16:17], off offset:-1536
	s_nop 1
	v_mov_b64_e32 v[16:17], v[80:81]
	v_mov_b64_e32 v[18:19], v[82:83]
	s_nop 0
	v_mov_b64_e32 v[20:21], v[64:65]
	v_mov_b64_e32 v[22:23], v[66:67]
	v_pk_mul_f32 v[26:27], v[4:5], v[24:25] op_sel_hi:[1,0]
	v_pk_mul_f32 v[28:29], v[6:7], v[24:25] op_sel_hi:[1,0]
	s_and_b64 vcc, exec, s[4:5]
	v_pk_add_f32 v[18:19], v[18:19], 1.0 op_sel_hi:[1,0]
	v_pk_add_f32 v[16:17], v[16:17], 1.0 op_sel_hi:[1,0]
	v_pk_fma_f32 v[18:19], v[18:19], v[28:29], v[22:23]
	v_pk_fma_f32 v[16:17], v[16:17], v[26:27], v[20:21]
	v_pk_mul_f32 v[26:27], v[8:9], v[24:25] op_sel_hi:[1,0]
	v_cvt_pk_bf16_f32 v16, v16, v17
	v_cvt_pk_bf16_f32 v17, v18, v19
	global_store_dwordx2 v[38:39], v[16:17], off offset:-1024
	s_nop 1
	v_mov_b64_e32 v[16:17], v[84:85]
	v_mov_b64_e32 v[18:19], v[86:87]
	s_nop 0
	v_mov_b64_e32 v[20:21], v[68:69]
	v_mov_b64_e32 v[22:23], v[70:71]
	v_pk_mul_f32 v[28:29], v[10:11], v[24:25] op_sel_hi:[1,0]
	v_pk_add_f32 v[18:19], v[18:19], 1.0 op_sel_hi:[1,0]
	v_pk_add_f32 v[16:17], v[16:17], 1.0 op_sel_hi:[1,0]
	v_pk_fma_f32 v[18:19], v[18:19], v[28:29], v[22:23]
	v_pk_fma_f32 v[16:17], v[16:17], v[26:27], v[20:21]
	v_pk_mul_f32 v[26:27], v[12:13], v[24:25] op_sel_hi:[1,0]
	v_cvt_pk_bf16_f32 v16, v16, v17
	v_cvt_pk_bf16_f32 v17, v18, v19
	global_store_dwordx2 v[38:39], v[16:17], off offset:-512
	s_nop 1
	v_mov_b64_e32 v[16:17], v[88:89]
	v_mov_b64_e32 v[18:19], v[90:91]
	s_nop 0
	v_mov_b64_e32 v[20:21], v[72:73]
	v_mov_b64_e32 v[22:23], v[74:75]
	v_pk_mul_f32 v[24:25], v[14:15], v[24:25] op_sel_hi:[1,0]
	v_pk_add_f32 v[18:19], v[18:19], 1.0 op_sel_hi:[1,0]
	v_pk_add_f32 v[16:17], v[16:17], 1.0 op_sel_hi:[1,0]
	v_pk_fma_f32 v[18:19], v[24:25], v[18:19], v[22:23]
	v_pk_fma_f32 v[16:17], v[26:27], v[16:17], v[20:21]
	s_nop 0
	v_cvt_pk_bf16_f32 v16, v16, v17
	v_cvt_pk_bf16_f32 v17, v18, v19
	global_store_dwordx2 v[38:39], v[16:17], off
	s_cbranch_vccnz .LBB0_1047
	v_add_co_u32_e32 v16, vcc, 0x1000, v46
	s_nop 1
	v_addc_co_u32_e32 v17, vcc, 0, v47, vcc
	global_store_dwordx4 v[16:17], v[0:3], off
	global_store_dwordx4 v[16:17], v[4:7], off offset:1024
	global_store_dwordx4 v[16:17], v[8:11], off offset:2048
	global_store_dwordx4 v[16:17], v[12:15], off offset:3072
	s_branch .LBB0_1047
